# residual epilogue: exact counted vmcnt per row (5/7/9: the per-row atomic always issues), so a row no longer waits for an earlier row's atomic to retire
# speedup vs baseline: 1.0003x; 1.0003x over previous
; DI unsigned pk2(float a, float b) { f32x2 v = {a, b}; bf16x2_t r = __builtin_convertvector(v, bf16x2_t); return __builtin_bit_cast(unsigned, r); }
; template <int NJ> DI void resid_epilogue(float* __restrict__ x, bf16_t* __restrict__ xb, float* __restrict__ ssn, int mt, int nt, const float* cl, float scale) {
;     ...
; #pragma unroll 4
;   for (int it = 0; it < NP; ++it) {
;     const int row = r0 + RPP * it;
;     const f32x4 c = *(const f32x4*)(cl + row * CLD + c4);
;     const size_t gi = (size_t)(mt * 128 + row) * DM + nt * (64 * NJ) + c4;
;     f32x4 xv = *(const f32x4*)(x + gi);
;     xv = xv + scale * c;
;     *(f32x4*)(x + gi) = xv;
;     u32x2 p; p.x = pk2(xv[0], xv[1]); p.y = pk2(xv[2], xv[3]);
;     *(u32x2*)(xb + (size_t)(mt * 128 + row) * LDX + nt * (64 * NJ) + c4) = p;
;     float s_ = xv[0] * xv[0] + xv[1] * xv[1] + xv[2] * xv[2] + xv[3] * xv[3];
;     if (NJ == 2) s_ += __shfl_xor(s_, 16);
;     s_ += __shfl_xor(s_, 8); s_ += __shfl_xor(s_, 4); s_ += __shfl_xor(s_, 2); s_ += __shfl_xor(s_, 1);
;     if ((tid & (LPR - 1)) == 0) atomicAdd(ssn + mt * 128 + row, s_);
;   }
.LBB0_431:
	s_or_b64 exec, exec, s[2:3]
	v_lshl_add_u64 v[36:37], v[16:17], 0, s[0:1]
	s_waitcnt lgkmcnt(0)
	ds_read_b128 v[32:35], v27 offset:4224
	s_waitcnt vmcnt(5) lgkmcnt(0)
	v_pk_fma_f32 v[32:33], v[32:33], 0.5, v[44:45] op_sel_hi:[1,0,1]
	s_nop 0
	v_mul_f32_e32 v0, v33, v33
	v_pk_fma_f32 v[34:35], v[34:35], 0.5, v[46:47] op_sel_hi:[1,0,1]
	v_fmac_f32_e32 v0, v32, v32
	v_fmac_f32_e32 v0, v34, v34
	v_fmac_f32_e32 v0, v35, v35
	ds_bpermute_b32 v28, v22, v0
	global_store_dwordx4 v[36:37], v[32:35], off
	v_cvt_pk_bf16_f32 v30, v32, v33
	v_cvt_pk_bf16_f32 v31, v34, v35
	v_lshl_add_u64 v[32:33], s[94:95], 0, v[14:15]
	s_waitcnt lgkmcnt(0)
	v_add_f32_e32 v0, v0, v28
	ds_bpermute_b32 v28, v23, v0
	global_store_dwordx2 v[32:33], v[30:31], off
	s_waitcnt lgkmcnt(0)
	v_add_f32_e32 v0, v0, v28
	ds_bpermute_b32 v28, v24, v0
	s_waitcnt lgkmcnt(0)
	v_add_f32_e32 v0, v0, v28
	ds_bpermute_b32 v28, v25, v0
	s_waitcnt lgkmcnt(0)
	v_add_f32_e32 v0, v0, v28
	ds_bpermute_b32 v28, v26, v0
	s_and_saveexec_b64 s[2:3], vcc
	s_cbranch_execz .LBB0_433
	s_waitcnt lgkmcnt(0)
	v_add_f32_e32 v0, v0, v28
	global_atomic_add_f32 v[20:21], v0, off offset:-32
.LBB0_433:
	s_or_b64 exec, exec, s[2:3]
	v_lshl_add_u64 v[36:37], v[10:11], 0, s[0:1]
	s_waitcnt lgkmcnt(0)
	ds_read_b128 v[32:35], v27 offset:8448
	s_waitcnt vmcnt(7) lgkmcnt(0)
	v_pk_fma_f32 v[32:33], v[32:33], 0.5, v[48:49] op_sel_hi:[1,0,1]
	s_nop 0
	v_mul_f32_e32 v0, v33, v33
	v_pk_fma_f32 v[34:35], v[34:35], 0.5, v[50:51] op_sel_hi:[1,0,1]
	v_fmac_f32_e32 v0, v32, v32
	v_fmac_f32_e32 v0, v34, v34
	v_fmac_f32_e32 v0, v35, v35
	ds_bpermute_b32 v28, v22, v0
	global_store_dwordx4 v[36:37], v[32:35], off
	v_cvt_pk_bf16_f32 v30, v32, v33
	v_cvt_pk_bf16_f32 v31, v34, v35
	v_lshl_add_u64 v[32:33], s[94:95], 0, v[8:9]
	s_waitcnt lgkmcnt(0)
	v_add_f32_e32 v0, v0, v28
	ds_bpermute_b32 v28, v23, v0
	global_store_dwordx2 v[32:33], v[30:31], off
	s_waitcnt lgkmcnt(0)
	v_add_f32_e32 v0, v0, v28
	ds_bpermute_b32 v28, v24, v0
	s_waitcnt lgkmcnt(0)
	v_add_f32_e32 v0, v0, v28
	ds_bpermute_b32 v28, v25, v0
	s_waitcnt lgkmcnt(0)
	v_add_f32_e32 v0, v0, v28
	ds_bpermute_b32 v28, v26, v0
	s_and_saveexec_b64 s[2:3], vcc
	s_cbranch_execz .LBB0_435
	s_waitcnt lgkmcnt(0)
	v_add_f32_e32 v0, v0, v28
	global_atomic_add_f32 v[20:21], v0, off
.LBB0_435:
	s_or_b64 exec, exec, s[2:3]
	v_lshl_add_u64 v[36:37], v[4:5], 0, s[0:1]
	s_waitcnt lgkmcnt(0)
	ds_read_b128 v[32:35], v27 offset:12672
	s_waitcnt vmcnt(9) lgkmcnt(0)
	v_pk_fma_f32 v[32:33], v[32:33], 0.5, v[52:53] op_sel_hi:[1,0,1]
	s_nop 0
	v_mul_f32_e32 v0, v33, v33
	v_pk_fma_f32 v[34:35], v[34:35], 0.5, v[54:55] op_sel_hi:[1,0,1]
	v_fmac_f32_e32 v0, v32, v32
	v_fmac_f32_e32 v0, v34, v34
	v_fmac_f32_e32 v0, v35, v35
	ds_bpermute_b32 v28, v22, v0
	global_store_dwordx4 v[36:37], v[32:35], off
	v_cvt_pk_bf16_f32 v30, v32, v33
	v_cvt_pk_bf16_f32 v31, v34, v35
	v_lshl_add_u64 v[32:33], s[94:95], 0, v[2:3]
	s_waitcnt lgkmcnt(0)
	v_add_f32_e32 v0, v0, v28
	ds_bpermute_b32 v28, v23, v0
	global_store_dwordx2 v[32:33], v[30:31], off
	s_waitcnt lgkmcnt(0)
	v_add_f32_e32 v0, v0, v28
	ds_bpermute_b32 v28, v24, v0
	s_waitcnt lgkmcnt(0)
	v_add_f32_e32 v0, v0, v28
	ds_bpermute_b32 v28, v25, v0
	s_waitcnt lgkmcnt(0)
	v_add_f32_e32 v0, v0, v28
	ds_bpermute_b32 v28, v26, v0
	s_and_saveexec_b64 s[2:3], vcc
	s_cbranch_execz .LBB0_428
	s_waitcnt lgkmcnt(0)
	v_add_f32_e32 v0, v0, v28
	global_atomic_add_f32 v[20:21], v0, off offset:32
	s_branch .LBB0_428

; DI unsigned pk2(float a, float b) { f32x2 v = {a, b}; bf16x2_t r = __builtin_convertvector(v, bf16x2_t); return __builtin_bit_cast(unsigned, r); }
; template <int NJ> DI void resid_epilogue(float* __restrict__ x, bf16_t* __restrict__ xb, float* __restrict__ ssn, int mt, int nt, const float* cl, float scale) {
;     ...
; #pragma unroll 4
;   for (int it = 0; it < NP; ++it) {
;     const int row = r0 + RPP * it;
;     const f32x4 c = *(const f32x4*)(cl + row * CLD + c4);
;     const size_t gi = (size_t)(mt * 128 + row) * DM + nt * (64 * NJ) + c4;
;     f32x4 xv = *(const f32x4*)(x + gi);
;     xv = xv + scale * c;
;     *(f32x4*)(x + gi) = xv;
;     u32x2 p; p.x = pk2(xv[0], xv[1]); p.y = pk2(xv[2], xv[3]);
;     *(u32x2*)(xb + (size_t)(mt * 128 + row) * LDX + nt * (64 * NJ) + c4) = p;
;     float s_ = xv[0] * xv[0] + xv[1] * xv[1] + xv[2] * xv[2] + xv[3] * xv[3];
;     if (NJ == 2) s_ += __shfl_xor(s_, 16);
;     s_ += __shfl_xor(s_, 8); s_ += __shfl_xor(s_, 4); s_ += __shfl_xor(s_, 2); s_ += __shfl_xor(s_, 1);
;     if ((tid & (LPR - 1)) == 0) atomicAdd(ssn + mt * 128 + row, s_);
;   }
.LBB0_1029:
	s_or_b64 exec, exec, s[2:3]
	v_lshl_add_u64 v[36:37], v[16:17], 0, s[0:1]
	s_waitcnt lgkmcnt(0)
	ds_read_b128 v[32:35], v27 offset:4224
	s_waitcnt vmcnt(5) lgkmcnt(0)
	v_pk_add_f32 v[32:33], v[32:33], v[44:45]
	s_nop 0
	v_mul_f32_e32 v0, v33, v33
	v_pk_add_f32 v[34:35], v[34:35], v[46:47]
	v_fmac_f32_e32 v0, v32, v32
	v_fmac_f32_e32 v0, v34, v34
	v_fmac_f32_e32 v0, v35, v35
	ds_bpermute_b32 v28, v22, v0
	global_store_dwordx4 v[36:37], v[32:35], off
	v_cvt_pk_bf16_f32 v30, v32, v33
	v_cvt_pk_bf16_f32 v31, v34, v35
	v_lshl_add_u64 v[32:33], s[94:95], 0, v[14:15]
	s_waitcnt lgkmcnt(0)
	v_add_f32_e32 v0, v0, v28
	ds_bpermute_b32 v28, v23, v0
	global_store_dwordx2 v[32:33], v[30:31], off
	s_waitcnt lgkmcnt(0)
	v_add_f32_e32 v0, v0, v28
	ds_bpermute_b32 v28, v24, v0
	s_waitcnt lgkmcnt(0)
	v_add_f32_e32 v0, v0, v28
	ds_bpermute_b32 v28, v25, v0
	s_waitcnt lgkmcnt(0)
	v_add_f32_e32 v0, v0, v28
	ds_bpermute_b32 v28, v26, v0
	s_and_saveexec_b64 s[2:3], vcc
	s_cbranch_execz .LBB0_1031
	s_waitcnt lgkmcnt(0)
	v_add_f32_e32 v0, v0, v28
	global_atomic_add_f32 v[20:21], v0, off offset:-32
.LBB0_1031:
	s_or_b64 exec, exec, s[2:3]
	v_lshl_add_u64 v[36:37], v[10:11], 0, s[0:1]
	s_waitcnt lgkmcnt(0)
	ds_read_b128 v[32:35], v27 offset:8448
	s_waitcnt vmcnt(7) lgkmcnt(0)
	v_pk_add_f32 v[32:33], v[32:33], v[48:49]
	s_nop 0
	v_mul_f32_e32 v0, v33, v33
	v_pk_add_f32 v[34:35], v[34:35], v[50:51]
	v_fmac_f32_e32 v0, v32, v32
	v_fmac_f32_e32 v0, v34, v34
	v_fmac_f32_e32 v0, v35, v35
	ds_bpermute_b32 v28, v22, v0
	global_store_dwordx4 v[36:37], v[32:35], off
	v_cvt_pk_bf16_f32 v30, v32, v33
	v_cvt_pk_bf16_f32 v31, v34, v35
	v_lshl_add_u64 v[32:33], s[94:95], 0, v[8:9]
	s_waitcnt lgkmcnt(0)
	v_add_f32_e32 v0, v0, v28
	ds_bpermute_b32 v28, v23, v0
	global_store_dwordx2 v[32:33], v[30:31], off
	s_waitcnt lgkmcnt(0)
	v_add_f32_e32 v0, v0, v28
	ds_bpermute_b32 v28, v24, v0
	s_waitcnt lgkmcnt(0)
	v_add_f32_e32 v0, v0, v28
	ds_bpermute_b32 v28, v25, v0
	s_waitcnt lgkmcnt(0)
	v_add_f32_e32 v0, v0, v28
	ds_bpermute_b32 v28, v26, v0
	s_and_saveexec_b64 s[2:3], vcc
	s_cbranch_execz .LBB0_1033
	s_waitcnt lgkmcnt(0)
	v_add_f32_e32 v0, v0, v28
	global_atomic_add_f32 v[20:21], v0, off
.LBB0_1033:
	s_or_b64 exec, exec, s[2:3]
	v_lshl_add_u64 v[36:37], v[4:5], 0, s[0:1]
	s_waitcnt lgkmcnt(0)
	ds_read_b128 v[32:35], v27 offset:12672
	s_waitcnt vmcnt(9) lgkmcnt(0)
	v_pk_add_f32 v[32:33], v[32:33], v[52:53]
	s_nop 0
	v_mul_f32_e32 v0, v33, v33
	v_pk_add_f32 v[34:35], v[34:35], v[54:55]
	v_fmac_f32_e32 v0, v32, v32
	v_fmac_f32_e32 v0, v34, v34
	v_fmac_f32_e32 v0, v35, v35
	ds_bpermute_b32 v28, v22, v0
	global_store_dwordx4 v[36:37], v[32:35], off
	v_cvt_pk_bf16_f32 v30, v32, v33
	v_cvt_pk_bf16_f32 v31, v34, v35
	v_lshl_add_u64 v[32:33], s[94:95], 0, v[2:3]
	s_waitcnt lgkmcnt(0)
	v_add_f32_e32 v0, v0, v28
	ds_bpermute_b32 v28, v23, v0
	global_store_dwordx2 v[32:33], v[30:31], off
	s_waitcnt lgkmcnt(0)
	v_add_f32_e32 v0, v0, v28
	ds_bpermute_b32 v28, v24, v0
	s_waitcnt lgkmcnt(0)
	v_add_f32_e32 v0, v0, v28
	ds_bpermute_b32 v28, v25, v0
	s_waitcnt lgkmcnt(0)
	v_add_f32_e32 v0, v0, v28
	ds_bpermute_b32 v28, v26, v0
	s_and_saveexec_b64 s[2:3], vcc
	s_cbranch_execz .LBB0_1026
	s_waitcnt lgkmcnt(0)
	v_add_f32_e32 v0, v0, v28
	global_atomic_add_f32 v[20:21], v0, off offset:32
	s_branch .LBB0_1026

; DI unsigned pk2(float a, float b) { f32x2 v = {a, b}; bf16x2_t r = __builtin_convertvector(v, bf16x2_t); return __builtin_bit_cast(unsigned, r); }
; template <int NJ> DI void resid_epilogue(float* __restrict__ x, bf16_t* __restrict__ xb, float* __restrict__ ssn, int mt, int nt, const float* cl, float scale) {
;     ...
; #pragma unroll 4
;   for (int it = 0; it < NP; ++it) {
;     const int row = r0 + RPP * it;
;     const f32x4 c = *(const f32x4*)(cl + row * CLD + c4);
;     const size_t gi = (size_t)(mt * 128 + row) * DM + nt * (64 * NJ) + c4;
;     f32x4 xv = *(const f32x4*)(x + gi);
;     xv = xv + scale * c;
;     *(f32x4*)(x + gi) = xv;
;     u32x2 p; p.x = pk2(xv[0], xv[1]); p.y = pk2(xv[2], xv[3]);
;     *(u32x2*)(xb + (size_t)(mt * 128 + row) * LDX + nt * (64 * NJ) + c4) = p;
;     float s_ = xv[0] * xv[0] + xv[1] * xv[1] + xv[2] * xv[2] + xv[3] * xv[3];
;     if (NJ == 2) s_ += __shfl_xor(s_, 16);
;     s_ += __shfl_xor(s_, 8); s_ += __shfl_xor(s_, 4); s_ += __shfl_xor(s_, 2); s_ += __shfl_xor(s_, 1);
;     if ((tid & (LPR - 1)) == 0) atomicAdd(ssn + mt * 128 + row, s_);
;   }
.LBB0_1230:
	s_or_b64 exec, exec, s[2:3]
	v_lshl_add_u64 v[36:37], v[16:17], 0, s[0:1]
	s_waitcnt lgkmcnt(0)
	ds_read_b128 v[32:35], v27 offset:4224
	s_waitcnt vmcnt(5) lgkmcnt(0)
	v_pk_add_f32 v[32:33], v[32:33], v[44:45]
	s_nop 0
	v_mul_f32_e32 v0, v33, v33
	v_pk_add_f32 v[34:35], v[34:35], v[46:47]
	v_fmac_f32_e32 v0, v32, v32
	v_fmac_f32_e32 v0, v34, v34
	v_fmac_f32_e32 v0, v35, v35
	ds_bpermute_b32 v28, v22, v0
	global_store_dwordx4 v[36:37], v[32:35], off
	v_cvt_pk_bf16_f32 v30, v32, v33
	v_cvt_pk_bf16_f32 v31, v34, v35
	v_lshl_add_u64 v[32:33], s[94:95], 0, v[14:15]
	s_waitcnt lgkmcnt(0)
	v_add_f32_e32 v0, v0, v28
	ds_bpermute_b32 v28, v23, v0
	global_store_dwordx2 v[32:33], v[30:31], off
	s_waitcnt lgkmcnt(0)
	v_add_f32_e32 v0, v0, v28
	ds_bpermute_b32 v28, v24, v0
	s_waitcnt lgkmcnt(0)
	v_add_f32_e32 v0, v0, v28
	ds_bpermute_b32 v28, v25, v0
	s_waitcnt lgkmcnt(0)
	v_add_f32_e32 v0, v0, v28
	ds_bpermute_b32 v28, v26, v0
	s_and_saveexec_b64 s[2:3], s[36:37]
	s_cbranch_execz .LBB0_1232
	s_waitcnt lgkmcnt(0)
	v_add_f32_e32 v0, v0, v28
	global_atomic_add_f32 v[20:21], v0, off offset:-32
.LBB0_1232:
	s_or_b64 exec, exec, s[2:3]
	v_lshl_add_u64 v[36:37], v[10:11], 0, s[0:1]
	s_waitcnt lgkmcnt(0)
	ds_read_b128 v[32:35], v27 offset:8448
	s_waitcnt vmcnt(7) lgkmcnt(0)
	v_pk_add_f32 v[32:33], v[32:33], v[48:49]
	s_nop 0
	v_mul_f32_e32 v0, v33, v33
	v_pk_add_f32 v[34:35], v[34:35], v[50:51]
	v_fmac_f32_e32 v0, v32, v32
	v_fmac_f32_e32 v0, v34, v34
	v_fmac_f32_e32 v0, v35, v35
	ds_bpermute_b32 v28, v22, v0
	global_store_dwordx4 v[36:37], v[32:35], off
	v_cvt_pk_bf16_f32 v30, v32, v33
	v_cvt_pk_bf16_f32 v31, v34, v35
	v_lshl_add_u64 v[32:33], s[94:95], 0, v[8:9]
	s_waitcnt lgkmcnt(0)
	v_add_f32_e32 v0, v0, v28
	ds_bpermute_b32 v28, v23, v0
	global_store_dwordx2 v[32:33], v[30:31], off
	s_waitcnt lgkmcnt(0)
	v_add_f32_e32 v0, v0, v28
	ds_bpermute_b32 v28, v24, v0
	s_waitcnt lgkmcnt(0)
	v_add_f32_e32 v0, v0, v28
	ds_bpermute_b32 v28, v25, v0
	s_waitcnt lgkmcnt(0)
	v_add_f32_e32 v0, v0, v28
	ds_bpermute_b32 v28, v26, v0
	s_and_saveexec_b64 s[2:3], s[36:37]
	s_cbranch_execz .LBB0_1234
	s_waitcnt lgkmcnt(0)
	v_add_f32_e32 v0, v0, v28
	global_atomic_add_f32 v[20:21], v0, off
.LBB0_1234:
	s_or_b64 exec, exec, s[2:3]
	v_lshl_add_u64 v[36:37], v[4:5], 0, s[0:1]
	s_waitcnt lgkmcnt(0)
	ds_read_b128 v[32:35], v27 offset:12672
	s_waitcnt vmcnt(9) lgkmcnt(0)
	v_pk_add_f32 v[32:33], v[32:33], v[52:53]
	s_nop 0
	v_mul_f32_e32 v0, v33, v33
	v_pk_add_f32 v[34:35], v[34:35], v[54:55]
	v_fmac_f32_e32 v0, v32, v32
	v_fmac_f32_e32 v0, v34, v34
	v_fmac_f32_e32 v0, v35, v35
	ds_bpermute_b32 v28, v22, v0
	global_store_dwordx4 v[36:37], v[32:35], off
	v_cvt_pk_bf16_f32 v30, v32, v33
	v_cvt_pk_bf16_f32 v31, v34, v35
	v_lshl_add_u64 v[32:33], s[94:95], 0, v[2:3]
	s_waitcnt lgkmcnt(0)
	v_add_f32_e32 v0, v0, v28
	ds_bpermute_b32 v28, v23, v0
	global_store_dwordx2 v[32:33], v[30:31], off
	s_waitcnt lgkmcnt(0)
	v_add_f32_e32 v0, v0, v28
	ds_bpermute_b32 v28, v24, v0
	s_waitcnt lgkmcnt(0)
	v_add_f32_e32 v0, v0, v28
	ds_bpermute_b32 v28, v25, v0
	s_waitcnt lgkmcnt(0)
	v_add_f32_e32 v0, v0, v28
	ds_bpermute_b32 v28, v26, v0
	s_and_saveexec_b64 s[2:3], s[36:37]
	s_cbranch_execz .LBB0_1227
	s_waitcnt lgkmcnt(0)
	v_add_f32_e32 v0, v0, v28
	global_atomic_add_f32 v[20:21], v0, off offset:32
	s_branch .LBB0_1227
